# attention loop-edge rotation: tile counters/alpha copy/loop test moved in front of the tile barrier; body-B first K reads issued right behind the barrier ahead of the post-barrier exps
# speedup vs baseline: 1.0076x; 1.0076x over previous
; #define SBAR() __builtin_amdgcn_sched_barrier(0)
; #define PK4(P, BASE, OUT) do { u32x4 w = {cvt_pk_bf16(P[BASE + 0], P[BASE + 1]), cvt_pk_bf16(P[BASE + 2], P[BASE + 3]), cvt_pk_bf16(P[BASE + 4], P[BASE + 5]), cvt_pk_bf16(P[BASE + 6], P[BASE + 7])}; \
;     OUT = *reinterpret_cast<bf16x8*>(&w); } while (0)
; #define SLOAD(i, k0) do { const bf16_t* vt_ = Vh + (size_t)(k0) * 512; const bf16_t* kt_ = KNh + (size_t)(k0) * 512; const bf16_t* rt_ = KRb + (size_t)(k0) * 32; \
;     sr_[i].vs = *reinterpret_cast<const bf16x8*>(vt_ + lo_kv); sr_[i].ks = *reinterpret_cast<const bf16x8*>(kt_ + lo_kv); sr_[i].kr = *reinterpret_cast<const s16x4*>(rt_ + lo_kr); } while (0)
; __device__ __forceinline__ void finishSM(f32x16& p0, f32x16& p1, float alpha, float& l_reg, bf16x8& pa0, bf16x8& pa1, bf16x8& pa2, bf16x8& pa3) {
; #pragma unroll
;   for (int r = 0; r < 16; ++r) p1[r] = __builtin_amdgcn_exp2f(p1[r]);
;   float ps = 0;
; #pragma unroll
;   for (int r = 0; r < 16; ++r) ps += p0[r];
; #pragma unroll
;   for (int r = 0; r < 16; ++r) ps += p1[r];
;   { auto rr = __builtin_amdgcn_permlane32_swap(__float_as_uint(ps), __float_as_uint(ps), false, false);
;     ps = __uint_as_float(rr[0]) + __uint_as_float(rr[1]); }
;   l_reg = l_reg * alpha + ps;
;     ...
;   PK4(p0, 0, pa0); PK4(p0, 8, pa1); PK4(p1, 0, pa2); PK4(p1, 8, pa3);
;     ...
; }
; __device__ __forceinline__ void qkt(f32x16& p0, f32x16& p1, const char* Ks, const bf16x8* qr, const f32x16& negm, int r32, int hi) {
;   p0 = negm; p1 = negm;
; #pragma unroll
;   for (int d0 = 0; d0 < 6; ++d0) { int cb = (d0 * 16 + hi * 8) * 2;
;     bf16x8 b0 = *reinterpret_cast<const bf16x8*>(Ks + KSWZ(r32, cb));
;     bf16x8 b1 = *reinterpret_cast<const bf16x8*>(Ks + KSWZ(32 + r32, cb));
;     p0 = __builtin_amdgcn_mfma_f32_32x32x16_bf16(b0, qr[d0], p0, 0, 0, 0);
;     p1 = __builtin_amdgcn_mfma_f32_32x32x16_bf16(b1, qr[d0], p1, 0, 0, 0); }
; }
; __device__ __forceinline__ void attn_unit(const bf16_t* __restrict__ Qb, const bf16_t* __restrict__ KNh, const bf16_t* __restrict__ KRb, const bf16_t* __restrict__ Vh, bf16_t* __restrict__ Ob, char* lds) {
;     ...
;     if (j + 2 < NT) { SWRITE((j + 2) & 3, 1); } if (j + 3 < NT) { SLOAD(0, (j + 3) * KVBLK); } SBAR();
.Lf1_746:
	s_waitcnt lgkmcnt(0)
	s_barrier
	s_add_i32 s46, s89, 0xffff8000
	s_and_b32 s46, s46, 0xc000
	s_add_i32 s46, s46, 0
	s_add_i32 s46, s46, 0x10000
	ds_read_b128 v[64:67], v243 offset:32768
	ds_read_b128 v[184:187], v243 offset:40960
	v_exp_f32_e32 v192, v96
	v_exp_f32_e32 v193, v97
	v_exp_f32_e32 v194, v98
	v_exp_f32_e32 v195, v99
	v_exp_f32_e32 v216, v100
	v_exp_f32_e32 v217, v101
	v_exp_f32_e32 v219, v102
	v_exp_f32_e32 v220, v103
	v_exp_f32_e32 v221, v104
	v_exp_f32_e32 v222, v105
	v_exp_f32_e32 v223, v106
	v_exp_f32_e32 v224, v107
	v_exp_f32_e32 v225, v108
	v_exp_f32_e32 v226, v109
	v_exp_f32_e32 v227, v110
	v_exp_f32_e32 v228, v111
	v_exp_f32_e32 v80, v80
	v_exp_f32_e32 v81, v81
	s_waitcnt lgkmcnt(1)
	v_mfma_f32_32x32x16_bf16 v[96:111], v[64:67], v[132:135], v[32:47]
	v_exp_f32_e32 v82, v82
	v_exp_f32_e32 v83, v83
	v_exp_f32_e32 v87, v87
	v_exp_f32_e32 v229, v92
	v_exp_f32_e32 v230, v93
	v_exp_f32_e32 v231, v94
	v_exp_f32_e32 v232, v95
	s_waitcnt lgkmcnt(0)
	v_mfma_f32_32x32x16_bf16 v[64:79], v[184:187], v[132:135], v[32:47]
	ds_read_b128 v[184:187], v244 offset:32768
	ds_read_b128 v[188:191], v244 offset:40960
	s_waitcnt lgkmcnt(1)
	v_mfma_f32_32x32x16_bf16 v[96:111], v[184:187], v[128:131], v[96:111]
	s_waitcnt lgkmcnt(0)
	v_mfma_f32_32x32x16_bf16 v[64:79], v[188:191], v[128:131], v[64:79]
	ds_read_b128 v[184:187], v245 offset:32768
	ds_read_b128 v[188:191], v245 offset:40960
	s_waitcnt lgkmcnt(1)
	v_mfma_f32_32x32x16_bf16 v[96:111], v[184:187], v[124:127], v[96:111]
	s_waitcnt lgkmcnt(0)
	v_mfma_f32_32x32x16_bf16 v[64:79], v[188:191], v[124:127], v[64:79]
	ds_read_b128 v[184:187], v246 offset:32768
	ds_read_b128 v[188:191], v246 offset:40960
	s_waitcnt lgkmcnt(1)
	v_mfma_f32_32x32x16_bf16 v[96:111], v[184:187], v[120:123], v[96:111]
	s_waitcnt lgkmcnt(0)
	v_mfma_f32_32x32x16_bf16 v[64:79], v[188:191], v[120:123], v[64:79]
	ds_read_b128 v[184:187], v247 offset:32768
	ds_read_b128 v[188:191], v247 offset:40960
	s_waitcnt lgkmcnt(1)
	v_mfma_f32_32x32x16_bf16 v[96:111], v[184:187], v[116:119], v[96:111]
	s_waitcnt lgkmcnt(0)
	v_mfma_f32_32x32x16_bf16 v[64:79], v[188:191], v[116:119], v[64:79]
	ds_read_b128 v[184:187], v248 offset:32768
	ds_read_b128 v[188:191], v248 offset:40960
	v_cvt_pk_bf16_f32 v92, v192, v193
	v_cvt_pk_bf16_f32 v93, v194, v195
	v_cvt_pk_bf16_f32 v94, v216, v217
	v_cvt_pk_bf16_f32 v95, v219, v220
	s_waitcnt lgkmcnt(1)
	v_mfma_f32_32x32x16_bf16 v[96:111], v[184:187], v[112:115], v[96:111]
	v_exp_f32_e32 v185, v84
	v_fma_f32 v84, v165, v169, v192
	v_add_f32_e32 v84, v193, v84
	v_add_f32_e32 v84, v194, v84
	v_add_f32_e32 v84, v195, v84
	v_add_f32_e32 v84, v216, v84
	v_add_f32_e32 v84, v217, v84
	v_add_f32_e32 v84, v219, v84
	v_add_f32_e32 v84, v220, v84
	v_add_f32_e32 v84, v221, v84
	v_add_f32_e32 v84, v222, v84
	v_add_f32_e32 v84, v223, v84
	v_add_f32_e32 v84, v224, v84
	v_add_f32_e32 v84, v225, v84
	v_add_f32_e32 v84, v226, v84
	v_add_f32_e32 v84, v227, v84
	v_add_f32_e32 v84, v228, v84
	v_add_f32_e32 v84, v80, v84
	v_exp_f32_e32 v186, v85
	v_add_f32_e32 v84, v81, v84
	v_exp_f32_e32 v187, v86
	v_add_f32_e32 v84, v82, v84
	v_add_f32_e32 v84, v83, v84
	s_waitcnt lgkmcnt(0)
	v_mfma_f32_32x32x16_bf16 v[64:79], v[188:191], v[112:115], v[64:79]
	v_exp_f32_e32 v188, v88
	v_add_f32_e32 v84, v185, v84
	v_exp_f32_e32 v189, v89
	v_add_f32_e32 v84, v186, v84
	v_exp_f32_e32 v190, v90
	v_add_f32_e32 v84, v187, v84
	v_exp_f32_e32 v191, v91
	v_add_f32_e32 v84, v87, v84
	v_add_f32_e32 v84, v188, v84
	v_add_f32_e32 v84, v189, v84
	v_add_f32_e32 v84, v190, v84
	v_add_f32_e32 v84, v191, v84
	v_add_f32_e32 v84, v229, v84
	v_add_f32_e32 v84, v230, v84
	v_add_f32_e32 v84, v231, v84
	v_add_f32_e32 v152, v232, v84
	v_cvt_pk_bf16_f32 v88, v221, v222
	v_cvt_pk_bf16_f32 v89, v223, v224
	v_cvt_pk_bf16_f32 v90, v225, v226
	v_cvt_pk_bf16_f32 v91, v227, v228
	v_cvt_pk_bf16_f32 v84, v80, v81
	v_cvt_pk_bf16_f32 v85, v82, v83
	v_cvt_pk_bf16_f32 v86, v185, v186
	v_cvt_pk_bf16_f32 v87, v187, v87
	v_cvt_pk_bf16_f32 v80, v188, v189
	v_cvt_pk_bf16_f32 v81, v190, v191
	v_cvt_pk_bf16_f32 v82, v229, v230
	v_cvt_pk_bf16_f32 v83, v231, v232
	s_add_i32 s44, s48, 0
	s_add_i32 s44, s44, 0x10000
	s_waitcnt vmcnt(2)
	ds_write_b128 v204, v[136:139]
	s_waitcnt vmcnt(1)
	ds_write_b128 v249, v[140:143]
	s_waitcnt vmcnt(0)
	ds_write_b64 v250, v[172:173]

; #define SBAR() __builtin_amdgcn_sched_barrier(0)
; #define PK4(P, BASE, OUT) do { u32x4 w = {cvt_pk_bf16(P[BASE + 0], P[BASE + 1]), cvt_pk_bf16(P[BASE + 2], P[BASE + 3]), cvt_pk_bf16(P[BASE + 4], P[BASE + 5]), cvt_pk_bf16(P[BASE + 6], P[BASE + 7])}; \
;     OUT = *reinterpret_cast<bf16x8*>(&w); } while (0)
; #define ABAR() asm volatile("s_waitcnt lgkmcnt(0)\n\ts_barrier" ::: "memory")
; template <bool FIRST> __device__ __forceinline__ void partialSM(f32x16& p0, f32x16& p1, float& mref, f32x16& negm, float& alpha) {
;     ...
;   for (int r = 0; r < 16; ++r) p0[r] = __builtin_amdgcn_exp2f(p0[r]);
; }
; __device__ __forceinline__ void finishSM(f32x16& p0, f32x16& p1, float alpha, float& l_reg, bf16x8& pa0, bf16x8& pa1, bf16x8& pa2, bf16x8& pa3) {
; #pragma unroll
;   for (int r = 0; r < 16; ++r) p1[r] = __builtin_amdgcn_exp2f(p1[r]);
;   float ps = 0;
; #pragma unroll
;   for (int r = 0; r < 16; ++r) ps += p0[r];
; #pragma unroll
;   for (int r = 0; r < 16; ++r) ps += p1[r];
;   { auto rr = __builtin_amdgcn_permlane32_swap(__float_as_uint(ps), __float_as_uint(ps), false, false);
;     ps = __uint_as_float(rr[0]) + __uint_as_float(rr[1]); }
;   l_reg = l_reg * alpha + ps;
;     ...
;   PK4(p0, 0, pa0); PK4(p0, 8, pa1); PK4(p1, 0, pa2); PK4(p1, 8, pa3);
;     ...
; }
; __device__ __forceinline__ void qkt(f32x16& p0, f32x16& p1, const char* Ks, const bf16x8* qr, const f32x16& negm, int r32, int hi) {
;   p0 = negm; p1 = negm;
; #pragma unroll
;   for (int d0 = 0; d0 < 6; ++d0) { int cb = (d0 * 16 + hi * 8) * 2;
;     bf16x8 b0 = *reinterpret_cast<const bf16x8*>(Ks + KSWZ(r32, cb));
;     bf16x8 b1 = *reinterpret_cast<const bf16x8*>(Ks + KSWZ(32 + r32, cb));
;     p0 = __builtin_amdgcn_mfma_f32_32x32x16_bf16(b0, qr[d0], p0, 0, 0, 0);
;     p1 = __builtin_amdgcn_mfma_f32_32x32x16_bf16(b1, qr[d0], p1, 0, 0, 0); }
; }
; __device__ __forceinline__ void attn_unit(const bf16_t* __restrict__ Qb, const bf16_t* __restrict__ KNh, const bf16_t* __restrict__ KRb, const bf16_t* __restrict__ Vh, bf16_t* __restrict__ Ob, char* lds) {
;     ...
;     SBAR(); qkt(pA0, pA1, K_lds + ((j + 1) & 3) * SHM_K, qr, negm, r32, hi);
;     finishSM(pB0, pB1, alB, l_reg, pa0, pa1, pa2, pa3); SBAR();
;     if (j + 3 < NT) { SWRITE((j + 3) & 3, 0); } if (j + 4 < NT) { SLOAD(1, (j + 4) * KVBLK); } SBAR();
;     pv_d0(o, vb0 + (j & 3) * SHM_V, pa0, pa1, pa2, pa3); partialSM<false>(pA0, pA1, mref, negm, alA);
;     RESC(alA); ABAR();
.Lf1_755:
	v_exp_f32_e32 v194, v96
	v_exp_f32_e32 v216, v97
	v_exp_f32_e32 v192, v98
	v_exp_f32_e32 v195, v99
	v_exp_f32_e32 v190, v100
	v_exp_f32_e32 v193, v101
	v_exp_f32_e32 v189, v102
	v_exp_f32_e32 v191, v103
	v_exp_f32_e32 v186, v104
	v_exp_f32_e32 v188, v105
	v_exp_f32_e32 v185, v106
	v_exp_f32_e32 v187, v107
	v_exp_f32_e32 v181, v108
	v_exp_f32_e32 v183, v109
	v_exp_f32_e32 v180, v110
	v_exp_f32_e32 v182, v111
	s_add_i32 s90, s90, 2
	s_add_i32 s89, s89, 0x8000
	v_mov_b32_e32 v163, v84
	s_waitcnt lgkmcnt(0)
	s_barrier
	s_add_i32 s41, s89, 0xffff4000
	s_and_b32 s41, s41, 0xc000
	s_add_i32 s42, s85, s41
	ds_read_b128 v[48:51], v243 offset:49152
	ds_read_b128 v[52:55], v243 offset:57344
	s_waitcnt lgkmcnt(1)
	v_mfma_f32_32x32x16_bf16 v[96:111], v[48:51], v[132:135], v[32:47]
	ds_read_b128 v[48:51], v244 offset:49152
	ds_read_b128 v[56:59], v244 offset:57344
	v_exp_f32_e32 v64, v64
	v_exp_f32_e32 v65, v65
	v_exp_f32_e32 v66, v66
	v_exp_f32_e32 v67, v67
	v_exp_f32_e32 v68, v68
	s_waitcnt lgkmcnt(2)
	v_mfma_f32_32x32x16_bf16 v[80:95], v[52:55], v[132:135], v[32:47]
	ds_read_b128 v[52:55], v245 offset:49152
	ds_read_b128 v[60:63], v245 offset:57344
	ds_read_b128 v[220:223], v246 offset:49152
	ds_read_b128 v[224:227], v246 offset:57344
	ds_read_b128 v[228:231], v247 offset:49152
	ds_read_b128 v[232:235], v247 offset:57344
	v_exp_f32_e32 v69, v69
	v_exp_f32_e32 v70, v70
	v_exp_f32_e32 v71, v71
	v_exp_f32_e32 v72, v72
	v_exp_f32_e32 v73, v73
	s_waitcnt lgkmcnt(7)
	v_mfma_f32_32x32x16_bf16 v[96:111], v[48:51], v[128:131], v[96:111]
	ds_read_b128 v[48:51], v248 offset:49152
	ds_read_b128 v[236:239], v248 offset:57344
	v_exp_f32_e32 v74, v74
	v_exp_f32_e32 v75, v75
	v_exp_f32_e32 v76, v76
	v_exp_f32_e32 v77, v77
	v_exp_f32_e32 v78, v78
	v_exp_f32_e32 v79, v79
	s_waitcnt lgkmcnt(8)
	v_mfma_f32_32x32x16_bf16 v[80:95], v[56:59], v[128:131], v[80:95]
	s_waitcnt lgkmcnt(7)
	v_mfma_f32_32x32x16_bf16 v[96:111], v[52:55], v[124:127], v[96:111]
	v_fma_f32 v52, v163, v152, v194
	v_add_f32_e32 v52, v216, v52
	v_add_f32_e32 v52, v192, v52
	v_add_f32_e32 v52, v195, v52
	v_add_f32_e32 v52, v190, v52
	v_add_f32_e32 v52, v193, v52
	v_add_f32_e32 v52, v189, v52
	s_waitcnt lgkmcnt(6)
	v_mfma_f32_32x32x16_bf16 v[80:95], v[60:63], v[124:127], v[80:95]
	v_add_f32_e32 v52, v191, v52
	v_add_f32_e32 v52, v186, v52
	v_add_f32_e32 v52, v188, v52
	v_add_f32_e32 v52, v185, v52
	v_add_f32_e32 v52, v187, v52
	v_add_f32_e32 v52, v181, v52
	v_add_f32_e32 v52, v183, v52
	s_waitcnt lgkmcnt(5)
	v_mfma_f32_32x32x16_bf16 v[96:111], v[220:223], v[120:123], v[96:111]
	v_add_f32_e32 v52, v180, v52
	v_add_f32_e32 v52, v182, v52
	v_add_f32_e32 v52, v64, v52
	v_add_f32_e32 v52, v65, v52
	v_add_f32_e32 v52, v66, v52
	v_add_f32_e32 v52, v67, v52
	v_add_f32_e32 v52, v68, v52
	s_waitcnt lgkmcnt(4)
	v_mfma_f32_32x32x16_bf16 v[80:95], v[224:227], v[120:123], v[80:95]
	v_add_f32_e32 v52, v69, v52
	v_add_f32_e32 v52, v70, v52
	v_add_f32_e32 v52, v71, v52
	v_add_f32_e32 v52, v72, v52
	v_add_f32_e32 v52, v73, v52
	v_add_f32_e32 v52, v74, v52
	v_add_f32_e32 v52, v75, v52
	s_waitcnt lgkmcnt(3)
	v_mfma_f32_32x32x16_bf16 v[96:111], v[228:231], v[116:119], v[96:111]
	v_add_f32_e32 v52, v76, v52
	v_add_f32_e32 v52, v77, v52
	v_add_f32_e32 v52, v78, v52
	v_add_f32_e32 v165, v79, v52
	s_waitcnt lgkmcnt(2)
	v_mfma_f32_32x32x16_bf16 v[80:95], v[232:235], v[116:119], v[80:95]
	v_cvt_pk_bf16_f32 v60, v194, v216
	v_cvt_pk_bf16_f32 v61, v192, v195
	v_cvt_pk_bf16_f32 v62, v190, v193
	v_cvt_pk_bf16_f32 v63, v189, v191
	v_cvt_pk_bf16_f32 v56, v186, v188
	v_cvt_pk_bf16_f32 v57, v185, v187
	v_cvt_pk_bf16_f32 v58, v181, v183
	s_waitcnt lgkmcnt(1)
	v_mfma_f32_32x32x16_bf16 v[96:111], v[48:51], v[112:115], v[96:111]
	v_cvt_pk_bf16_f32 v59, v180, v182
	v_cvt_pk_bf16_f32 v52, v64, v65
	v_cvt_pk_bf16_f32 v53, v66, v67
	v_cvt_pk_bf16_f32 v54, v68, v69
	v_cvt_pk_bf16_f32 v55, v70, v71
	v_cvt_pk_bf16_f32 v48, v72, v73
	v_cvt_pk_bf16_f32 v49, v74, v75
	s_waitcnt lgkmcnt(0)
	v_mfma_f32_32x32x16_bf16 v[80:95], v[236:239], v[112:115], v[80:95]
	v_cvt_pk_bf16_f32 v50, v76, v77
	v_cvt_pk_bf16_f32 v51, v78, v79
	s_add_i32 s42, s89, 0xffffc000
	s_and_b32 s42, s42, 0xc000
	s_add_i32 s43, s85, s42
	s_and_b64 vcc, exec, s[42:43]
	s_waitcnt vmcnt(2)
	ds_write_b128 v204, v[144:147] offset:16384
	s_waitcnt vmcnt(1)
	ds_write_b128 v249, v[148:151] offset:16384
	s_waitcnt vmcnt(0)
	ds_write_b64 v250, v[174:175] offset:16384
	global_load_dwordx4 v[136:139], v240, s[98:99]
	global_load_dwordx4 v[140:143], v241, s[98:99]
	global_load_dwordx2 v[172:173], v242, s[100:101]
	s_add_u32 s98, s98, 0x10000
	s_addc_u32 s99, s99, 0
	s_add_u32 s100, s100, 0x1000
	s_addc_u32 s101, s101, 0

; #define SBAR() __builtin_amdgcn_sched_barrier(0)
; #define PK4(P, BASE, OUT) do { u32x4 w = {cvt_pk_bf16(P[BASE + 0], P[BASE + 1]), cvt_pk_bf16(P[BASE + 2], P[BASE + 3]), cvt_pk_bf16(P[BASE + 4], P[BASE + 5]), cvt_pk_bf16(P[BASE + 6], P[BASE + 7])}; \
;     OUT = *reinterpret_cast<bf16x8*>(&w); } while (0)
; #define SLOAD(i, k0) do { const bf16_t* vt_ = Vh + (size_t)(k0) * 512; const bf16_t* kt_ = KNh + (size_t)(k0) * 512; const bf16_t* rt_ = KRb + (size_t)(k0) * 32; \
;     sr_[i].vs = *reinterpret_cast<const bf16x8*>(vt_ + lo_kv); sr_[i].ks = *reinterpret_cast<const bf16x8*>(kt_ + lo_kv); sr_[i].kr = *reinterpret_cast<const s16x4*>(rt_ + lo_kr); } while (0)
; __device__ __forceinline__ void finishSM(f32x16& p0, f32x16& p1, float alpha, float& l_reg, bf16x8& pa0, bf16x8& pa1, bf16x8& pa2, bf16x8& pa3) {
; #pragma unroll
;   for (int r = 0; r < 16; ++r) p1[r] = __builtin_amdgcn_exp2f(p1[r]);
;   float ps = 0;
; #pragma unroll
;   for (int r = 0; r < 16; ++r) ps += p0[r];
; #pragma unroll
;   for (int r = 0; r < 16; ++r) ps += p1[r];
;   { auto rr = __builtin_amdgcn_permlane32_swap(__float_as_uint(ps), __float_as_uint(ps), false, false);
;     ps = __uint_as_float(rr[0]) + __uint_as_float(rr[1]); }
;   l_reg = l_reg * alpha + ps;
;     ...
;   PK4(p0, 0, pa0); PK4(p0, 8, pa1); PK4(p1, 0, pa2); PK4(p1, 8, pa3);
;     ...
; }
; __device__ __forceinline__ void qkt(f32x16& p0, f32x16& p1, const char* Ks, const bf16x8* qr, const f32x16& negm, int r32, int hi) {
;   p0 = negm; p1 = negm;
; #pragma unroll
;   for (int d0 = 0; d0 < 6; ++d0) { int cb = (d0 * 16 + hi * 8) * 2;
;     bf16x8 b0 = *reinterpret_cast<const bf16x8*>(Ks + KSWZ(r32, cb));
;     bf16x8 b1 = *reinterpret_cast<const bf16x8*>(Ks + KSWZ(32 + r32, cb));
;     p0 = __builtin_amdgcn_mfma_f32_32x32x16_bf16(b0, qr[d0], p0, 0, 0, 0);
;     p1 = __builtin_amdgcn_mfma_f32_32x32x16_bf16(b1, qr[d0], p1, 0, 0, 0); }
; }
; __device__ __forceinline__ void attn_unit(const bf16_t* __restrict__ Qb, const bf16_t* __restrict__ KNh, const bf16_t* __restrict__ KRb, const bf16_t* __restrict__ Vh, bf16_t* __restrict__ Ob, char* lds) {
;     ...
;     if (j + 2 < NT) { SWRITE((j + 2) & 3, 1); } if (j + 3 < NT) { SLOAD(0, (j + 3) * KVBLK); } SBAR();
.Lf2_746:
	s_waitcnt lgkmcnt(0)
	s_barrier
	s_add_i32 s46, s89, 0xffff8000
	s_and_b32 s46, s46, 0xc000
	s_add_i32 s46, s46, 0
	s_add_i32 s46, s46, 0x10000
	ds_read_b128 v[64:67], v243
	ds_read_b128 v[184:187], v243 offset:8192
	v_exp_f32_e32 v192, v96
	v_exp_f32_e32 v193, v97
	v_exp_f32_e32 v194, v98
	v_exp_f32_e32 v195, v99
	v_exp_f32_e32 v216, v100
	v_exp_f32_e32 v217, v101
	v_exp_f32_e32 v219, v102
	v_exp_f32_e32 v220, v103
	v_exp_f32_e32 v221, v104
	v_exp_f32_e32 v222, v105
	v_exp_f32_e32 v223, v106
	v_exp_f32_e32 v224, v107
	v_exp_f32_e32 v225, v108
	v_exp_f32_e32 v226, v109
	v_exp_f32_e32 v227, v110
	v_exp_f32_e32 v228, v111
	v_exp_f32_e32 v80, v80
	v_exp_f32_e32 v81, v81
	s_waitcnt lgkmcnt(1)
	v_mfma_f32_32x32x16_bf16 v[96:111], v[64:67], v[132:135], v[32:47]
	v_exp_f32_e32 v82, v82
	v_exp_f32_e32 v83, v83
	v_exp_f32_e32 v87, v87
	v_exp_f32_e32 v229, v92
	v_exp_f32_e32 v230, v93
	v_exp_f32_e32 v231, v94
	v_exp_f32_e32 v232, v95
	s_waitcnt lgkmcnt(0)
	v_mfma_f32_32x32x16_bf16 v[64:79], v[184:187], v[132:135], v[32:47]
	ds_read_b128 v[184:187], v244
	ds_read_b128 v[188:191], v244 offset:8192
	s_waitcnt lgkmcnt(1)
	v_mfma_f32_32x32x16_bf16 v[96:111], v[184:187], v[128:131], v[96:111]
	s_waitcnt lgkmcnt(0)
	v_mfma_f32_32x32x16_bf16 v[64:79], v[188:191], v[128:131], v[64:79]
	ds_read_b128 v[184:187], v245
	ds_read_b128 v[188:191], v245 offset:8192
	s_waitcnt lgkmcnt(1)
	v_mfma_f32_32x32x16_bf16 v[96:111], v[184:187], v[124:127], v[96:111]
	s_waitcnt lgkmcnt(0)
	v_mfma_f32_32x32x16_bf16 v[64:79], v[188:191], v[124:127], v[64:79]
	ds_read_b128 v[184:187], v246
	ds_read_b128 v[188:191], v246 offset:8192
	s_waitcnt lgkmcnt(1)
	v_mfma_f32_32x32x16_bf16 v[96:111], v[184:187], v[120:123], v[96:111]
	s_waitcnt lgkmcnt(0)
	v_mfma_f32_32x32x16_bf16 v[64:79], v[188:191], v[120:123], v[64:79]
	ds_read_b128 v[184:187], v247
	ds_read_b128 v[188:191], v247 offset:8192
	s_waitcnt lgkmcnt(1)
	v_mfma_f32_32x32x16_bf16 v[96:111], v[184:187], v[116:119], v[96:111]
	s_waitcnt lgkmcnt(0)
	v_mfma_f32_32x32x16_bf16 v[64:79], v[188:191], v[116:119], v[64:79]
	ds_read_b128 v[184:187], v248
	ds_read_b128 v[188:191], v248 offset:8192
	v_cvt_pk_bf16_f32 v92, v192, v193
	v_cvt_pk_bf16_f32 v93, v194, v195
	v_cvt_pk_bf16_f32 v94, v216, v217
	v_cvt_pk_bf16_f32 v95, v219, v220
	s_waitcnt lgkmcnt(1)
	v_mfma_f32_32x32x16_bf16 v[96:111], v[184:187], v[112:115], v[96:111]
	v_exp_f32_e32 v185, v84
	v_fma_f32 v84, v165, v169, v192
	v_add_f32_e32 v84, v193, v84
	v_add_f32_e32 v84, v194, v84
	v_add_f32_e32 v84, v195, v84
	v_add_f32_e32 v84, v216, v84
	v_add_f32_e32 v84, v217, v84
	v_add_f32_e32 v84, v219, v84
	v_add_f32_e32 v84, v220, v84
	v_add_f32_e32 v84, v221, v84
	v_add_f32_e32 v84, v222, v84
	v_add_f32_e32 v84, v223, v84
	v_add_f32_e32 v84, v224, v84
	v_add_f32_e32 v84, v225, v84
	v_add_f32_e32 v84, v226, v84
	v_add_f32_e32 v84, v227, v84
	v_add_f32_e32 v84, v228, v84
	v_add_f32_e32 v84, v80, v84
	v_exp_f32_e32 v186, v85
	v_add_f32_e32 v84, v81, v84
	v_exp_f32_e32 v187, v86
	v_add_f32_e32 v84, v82, v84
	v_add_f32_e32 v84, v83, v84
	s_waitcnt lgkmcnt(0)
	v_mfma_f32_32x32x16_bf16 v[64:79], v[188:191], v[112:115], v[64:79]
	v_exp_f32_e32 v188, v88
	v_add_f32_e32 v84, v185, v84
	v_exp_f32_e32 v189, v89
	v_add_f32_e32 v84, v186, v84
	v_exp_f32_e32 v190, v90
	v_add_f32_e32 v84, v187, v84
	v_exp_f32_e32 v191, v91
	v_add_f32_e32 v84, v87, v84
	v_add_f32_e32 v84, v188, v84
	v_add_f32_e32 v84, v189, v84
	v_add_f32_e32 v84, v190, v84
	v_add_f32_e32 v84, v191, v84
	v_add_f32_e32 v84, v229, v84
	v_add_f32_e32 v84, v230, v84
	v_add_f32_e32 v84, v231, v84
	v_add_f32_e32 v152, v232, v84
	v_cvt_pk_bf16_f32 v88, v221, v222
	v_cvt_pk_bf16_f32 v89, v223, v224
	v_cvt_pk_bf16_f32 v90, v225, v226
	v_cvt_pk_bf16_f32 v91, v227, v228
	v_cvt_pk_bf16_f32 v84, v80, v81
	v_cvt_pk_bf16_f32 v85, v82, v83
	v_cvt_pk_bf16_f32 v86, v185, v186
	v_cvt_pk_bf16_f32 v87, v187, v87
	v_cvt_pk_bf16_f32 v80, v188, v189
	v_cvt_pk_bf16_f32 v81, v190, v191
	v_cvt_pk_bf16_f32 v82, v229, v230
	v_cvt_pk_bf16_f32 v83, v231, v232
	s_add_i32 s44, s48, 0
	s_add_i32 s44, s44, 0x10000
	s_waitcnt vmcnt(2)
	ds_write_b128 v204, v[136:139] offset:32768
	s_waitcnt vmcnt(1)
	ds_write_b128 v249, v[140:143] offset:32768
	s_waitcnt vmcnt(0)
	ds_write_b64 v250, v[172:173] offset:32768

; #define SBAR() __builtin_amdgcn_sched_barrier(0)
; #define ABAR() asm volatile("s_waitcnt lgkmcnt(0)\n\ts_barrier" ::: "memory")
; #define SLOAD(i, k0) do { const bf16_t* vt_ = Vh + (size_t)(k0) * 512; const bf16_t* kt_ = KNh + (size_t)(k0) * 512; const bf16_t* rt_ = KRb + (size_t)(k0) * 32; \
;     sr_[i].vs = *reinterpret_cast<const bf16x8*>(vt_ + lo_kv); sr_[i].ks = *reinterpret_cast<const bf16x8*>(kt_ + lo_kv); sr_[i].kr = *reinterpret_cast<const s16x4*>(rt_ + lo_kr); } while (0)
; #define SWRITE(slot, i) do { *(bf16x8*)(V_lds + (slot) * SHM_V + vst) = sr_[i].vs; *(bf16x8*)(K_lds + (slot) * SHM_K + kst) = sr_[i].ks; *(s16x4*)(K_lds + (slot) * SHM_K + krst) = sr_[i].kr; } while (0)
; #define RESC(a) do { if (__any((a) < 1.f)) { if (hi == 0) al_l[r32] = (a); asm volatile("s_waitcnt lgkmcnt(0)" ::: "memory"); \
;     _Pragma("unroll") for (int d = 0; d < 2; ++d) _Pragma("unroll") for (int r = 0; r < 16; ++r) o[d][r] *= al_l[crow(r, hi)]; } } while (0)
; __device__ __forceinline__ void attn_unit(const bf16_t* __restrict__ Qb, const bf16_t* __restrict__ KNh, const bf16_t* __restrict__ KRb, const bf16_t* __restrict__ Vh, bf16_t* __restrict__ Ob, char* lds) {
;     ...
;   for (int j = 1; j + 1 < NT; j += 2) {
;     SBAR(); qkt(pB0, pB1, K_lds + (j & 3) * SHM_K, qr, negm, r32, hi);
;     finishSM(pA0, pA1, alA, l_reg, pa0, pa1, pa2, pa3); SBAR();
;     if (j + 2 < NT) { SWRITE((j + 2) & 3, 1); } if (j + 3 < NT) { SLOAD(0, (j + 3) * KVBLK); } SBAR();
;     pv_d0(o, vb0 + ((j - 1) & 3) * SHM_V, pa0, pa1, pa2, pa3); partialSM<false>(pB0, pB1, mref, negm, alB);
;     RESC(alB); ABAR();
;     SBAR(); qkt(pA0, pA1, K_lds + ((j + 1) & 3) * SHM_K, qr, negm, r32, hi);
;     finishSM(pB0, pB1, alB, l_reg, pa0, pa1, pa2, pa3); SBAR();
;     if (j + 3 < NT) { SWRITE((j + 3) & 3, 0); } if (j + 4 < NT) { SLOAD(1, (j + 4) * KVBLK); } SBAR();
;     pv_d0(o, vb0 + (j & 3) * SHM_V, pa0, pa1, pa2, pa3); partialSM<false>(pA0, pA1, mref, negm, alA);
;     RESC(alA); ABAR();
.Lf2_755:
	v_exp_f32_e32 v194, v96
	v_exp_f32_e32 v216, v97
	v_exp_f32_e32 v192, v98
	v_exp_f32_e32 v195, v99
	v_exp_f32_e32 v190, v100
	v_exp_f32_e32 v193, v101
	v_exp_f32_e32 v189, v102
	v_exp_f32_e32 v191, v103
	v_exp_f32_e32 v186, v104
	v_exp_f32_e32 v188, v105
	v_exp_f32_e32 v185, v106
	v_exp_f32_e32 v187, v107
	v_exp_f32_e32 v181, v108
	v_exp_f32_e32 v183, v109
	v_exp_f32_e32 v180, v110
	v_exp_f32_e32 v182, v111
	s_add_i32 s90, s90, 2
	s_add_i32 s89, s89, 0x8000
	v_mov_b32_e32 v163, v84
	s_cmp_lt_u32 s90, 26
	s_waitcnt lgkmcnt(0)
	s_barrier
	s_cbranch_scc1 .Lattn_f4

; #define SBAR() __builtin_amdgcn_sched_barrier(0)
; #define PK4(P, BASE, OUT) do { u32x4 w = {cvt_pk_bf16(P[BASE + 0], P[BASE + 1]), cvt_pk_bf16(P[BASE + 2], P[BASE + 3]), cvt_pk_bf16(P[BASE + 4], P[BASE + 5]), cvt_pk_bf16(P[BASE + 6], P[BASE + 7])}; \
;     OUT = *reinterpret_cast<bf16x8*>(&w); } while (0)
; #define SLOAD(i, k0) do { const bf16_t* vt_ = Vh + (size_t)(k0) * 512; const bf16_t* kt_ = KNh + (size_t)(k0) * 512; const bf16_t* rt_ = KRb + (size_t)(k0) * 32; \
;     sr_[i].vs = *reinterpret_cast<const bf16x8*>(vt_ + lo_kv); sr_[i].ks = *reinterpret_cast<const bf16x8*>(kt_ + lo_kv); sr_[i].kr = *reinterpret_cast<const s16x4*>(rt_ + lo_kr); } while (0)
; __device__ __forceinline__ void finishSM(f32x16& p0, f32x16& p1, float alpha, float& l_reg, bf16x8& pa0, bf16x8& pa1, bf16x8& pa2, bf16x8& pa3) {
; #pragma unroll
;   for (int r = 0; r < 16; ++r) p1[r] = __builtin_amdgcn_exp2f(p1[r]);
;   float ps = 0;
; #pragma unroll
;   for (int r = 0; r < 16; ++r) ps += p0[r];
; #pragma unroll
;   for (int r = 0; r < 16; ++r) ps += p1[r];
;   { auto rr = __builtin_amdgcn_permlane32_swap(__float_as_uint(ps), __float_as_uint(ps), false, false);
;     ps = __uint_as_float(rr[0]) + __uint_as_float(rr[1]); }
;   l_reg = l_reg * alpha + ps;
;     ...
;   PK4(p0, 0, pa0); PK4(p0, 8, pa1); PK4(p1, 0, pa2); PK4(p1, 8, pa3);
;     ...
; }
; __device__ __forceinline__ void qkt(f32x16& p0, f32x16& p1, const char* Ks, const bf16x8* qr, const f32x16& negm, int r32, int hi) {
;   p0 = negm; p1 = negm;
; #pragma unroll
;   for (int d0 = 0; d0 < 6; ++d0) { int cb = (d0 * 16 + hi * 8) * 2;
;     bf16x8 b0 = *reinterpret_cast<const bf16x8*>(Ks + KSWZ(r32, cb));
;     bf16x8 b1 = *reinterpret_cast<const bf16x8*>(Ks + KSWZ(32 + r32, cb));
;     p0 = __builtin_amdgcn_mfma_f32_32x32x16_bf16(b0, qr[d0], p0, 0, 0, 0);
;     p1 = __builtin_amdgcn_mfma_f32_32x32x16_bf16(b1, qr[d0], p1, 0, 0, 0); }
; }
; __device__ __forceinline__ void attn_unit(const bf16_t* __restrict__ Qb, const bf16_t* __restrict__ KNh, const bf16_t* __restrict__ KRb, const bf16_t* __restrict__ Vh, bf16_t* __restrict__ Ob, char* lds) {
;     ...
;     if (j + 2 < NT) { SWRITE((j + 2) & 3, 1); } if (j + 3 < NT) { SLOAD(0, (j + 3) * KVBLK); } SBAR();
.LBB0_746:
	s_waitcnt lgkmcnt(0)
	s_barrier
	s_add_i32 s46, s89, 0xffff8000
	s_and_b32 s46, s46, 0xc000
	s_add_i32 s46, s46, 0
	s_add_i32 s46, s46, 0x10000
	v_add_u32_e32 v68, s46, v206
	ds_read_b128 v[64:67], v68
	ds_read_b128 v[184:187], v68 offset:8192
	v_exp_f32_e32 v192, v96
	v_exp_f32_e32 v193, v97
	v_exp_f32_e32 v194, v98
	v_exp_f32_e32 v195, v99
	v_exp_f32_e32 v216, v100
	v_exp_f32_e32 v217, v101
	v_exp_f32_e32 v219, v102
	v_exp_f32_e32 v220, v103
	v_exp_f32_e32 v221, v104
	v_exp_f32_e32 v222, v105
	v_exp_f32_e32 v223, v106
	v_exp_f32_e32 v224, v107
	v_exp_f32_e32 v225, v108
	v_exp_f32_e32 v226, v109
	v_exp_f32_e32 v227, v110
	v_exp_f32_e32 v228, v111
	v_add_u32_e32 v171, s46, v207
	v_exp_f32_e32 v80, v80
	v_exp_f32_e32 v81, v81
	s_waitcnt lgkmcnt(1)
	v_mfma_f32_32x32x16_bf16 v[96:111], v[64:67], v[132:135], v[32:47]
	v_exp_f32_e32 v82, v82
	v_exp_f32_e32 v83, v83
	v_exp_f32_e32 v87, v87
	v_exp_f32_e32 v229, v92
	v_exp_f32_e32 v230, v93
	v_exp_f32_e32 v231, v94
	v_exp_f32_e32 v232, v95
	s_waitcnt lgkmcnt(0)
	v_mfma_f32_32x32x16_bf16 v[64:79], v[184:187], v[132:135], v[32:47]
	ds_read_b128 v[184:187], v171
	ds_read_b128 v[188:191], v171 offset:8192
	v_add_u32_e32 v171, s46, v208
	s_waitcnt lgkmcnt(1)
	v_mfma_f32_32x32x16_bf16 v[96:111], v[184:187], v[128:131], v[96:111]
	s_waitcnt lgkmcnt(0)
	v_mfma_f32_32x32x16_bf16 v[64:79], v[188:191], v[128:131], v[64:79]
	ds_read_b128 v[184:187], v171
	ds_read_b128 v[188:191], v171 offset:8192
	v_add_u32_e32 v171, s46, v209
	s_waitcnt lgkmcnt(1)
	v_mfma_f32_32x32x16_bf16 v[96:111], v[184:187], v[124:127], v[96:111]
	s_waitcnt lgkmcnt(0)
	v_mfma_f32_32x32x16_bf16 v[64:79], v[188:191], v[124:127], v[64:79]
	ds_read_b128 v[184:187], v171
	ds_read_b128 v[188:191], v171 offset:8192
	v_add_u32_e32 v171, s46, v210
	s_waitcnt lgkmcnt(1)
	v_mfma_f32_32x32x16_bf16 v[96:111], v[184:187], v[120:123], v[96:111]
	s_waitcnt lgkmcnt(0)
	v_mfma_f32_32x32x16_bf16 v[64:79], v[188:191], v[120:123], v[64:79]
	ds_read_b128 v[184:187], v171
	ds_read_b128 v[188:191], v171 offset:8192
	v_add_u32_e32 v171, s46, v211
	s_waitcnt lgkmcnt(1)
	v_mfma_f32_32x32x16_bf16 v[96:111], v[184:187], v[116:119], v[96:111]
	s_waitcnt lgkmcnt(0)
	v_mfma_f32_32x32x16_bf16 v[64:79], v[188:191], v[116:119], v[64:79]
	ds_read_b128 v[184:187], v171
	ds_read_b128 v[188:191], v171 offset:8192
	v_cvt_pk_bf16_f32 v92, v192, v193
	v_cvt_pk_bf16_f32 v93, v194, v195
	v_cvt_pk_bf16_f32 v94, v216, v217
	v_cvt_pk_bf16_f32 v95, v219, v220
	s_waitcnt lgkmcnt(1)
	v_mfma_f32_32x32x16_bf16 v[96:111], v[184:187], v[112:115], v[96:111]
	v_exp_f32_e32 v185, v84
	v_fma_f32 v84, v165, v169, v192
	v_add_f32_e32 v84, v193, v84
	v_add_f32_e32 v84, v194, v84
	v_add_f32_e32 v84, v195, v84
	v_add_f32_e32 v84, v216, v84
	v_add_f32_e32 v84, v217, v84
	v_add_f32_e32 v84, v219, v84
	v_add_f32_e32 v84, v220, v84
	v_add_f32_e32 v84, v221, v84
	v_add_f32_e32 v84, v222, v84
	v_add_f32_e32 v84, v223, v84
	v_add_f32_e32 v84, v224, v84
	v_add_f32_e32 v84, v225, v84
	v_add_f32_e32 v84, v226, v84
	v_add_f32_e32 v84, v227, v84
	v_add_f32_e32 v84, v228, v84
	v_add_f32_e32 v84, v80, v84
	v_exp_f32_e32 v186, v85
	v_add_f32_e32 v84, v81, v84
	v_exp_f32_e32 v187, v86
	v_add_f32_e32 v84, v82, v84
	v_add_f32_e32 v84, v83, v84
	s_waitcnt lgkmcnt(0)
	v_mfma_f32_32x32x16_bf16 v[64:79], v[188:191], v[112:115], v[64:79]
	v_exp_f32_e32 v188, v88
	v_add_f32_e32 v84, v185, v84
	v_exp_f32_e32 v189, v89
	v_add_f32_e32 v84, v186, v84
	v_exp_f32_e32 v190, v90
	v_add_f32_e32 v84, v187, v84
	v_exp_f32_e32 v191, v91
	v_add_f32_e32 v84, v87, v84
	v_add_f32_e32 v84, v188, v84
	v_add_f32_e32 v84, v189, v84
	v_add_f32_e32 v84, v190, v84
	v_add_f32_e32 v84, v191, v84
	v_add_f32_e32 v84, v229, v84
	v_add_f32_e32 v84, v230, v84
	v_add_f32_e32 v84, v231, v84
	v_add_f32_e32 v152, v232, v84
	v_cvt_pk_bf16_f32 v88, v221, v222
	v_cvt_pk_bf16_f32 v89, v223, v224
	v_cvt_pk_bf16_f32 v90, v225, v226
	v_cvt_pk_bf16_f32 v91, v227, v228
	v_cvt_pk_bf16_f32 v84, v80, v81
	v_cvt_pk_bf16_f32 v85, v82, v83
	v_cvt_pk_bf16_f32 v86, v185, v186
	v_cvt_pk_bf16_f32 v87, v187, v87
	v_cvt_pk_bf16_f32 v80, v188, v189
	v_cvt_pk_bf16_f32 v81, v190, v191
	v_cvt_pk_bf16_f32 v82, v229, v230
	v_cvt_pk_bf16_f32 v83, v231, v232
	s_andn2_b64 vcc, exec, s[44:45]
	s_cbranch_vccnz .LBB0_748
	s_add_i32 s44, s48, 0
	v_add_u32_e32 v185, s48, v204
	s_add_i32 s44, s44, 0x10000
	v_add_u32_e32 v186, s44, v201
	v_add_u32_e32 v187, s44, v202
	s_waitcnt vmcnt(2)
	ds_write_b128 v185, v[136:139]
	s_waitcnt vmcnt(1)
	ds_write_b128 v186, v[140:143]
	s_waitcnt vmcnt(0)
	ds_write_b64 v187, v[172:173]
